# write-through strategy: sc1 on the 16-byte P tile stores (P1) and transpose stores (P0) so the phase-end L2 writeback has less dirty data
# baseline (speedup 1.0000x reference)
.Ltr_a_end:
	v_mad_u32_u24 v4, v78, s12, v1
	v_mad_u32_u24 v5, v79, s12, v1
	v_mad_u32_u24 v6, v80, s12, v1
	v_mad_u32_u24 v7, v81, s12, v1
	global_load_dwordx4 v[32:35], v4, s[10:11]
	global_load_dwordx4 v[36:39], v5, s[10:11]
	global_load_dwordx4 v[40:43], v6, s[10:11]
	global_load_dwordx4 v[44:47], v7, s[10:11]
	s_waitcnt vmcnt(4)
	ds_write2_b32 v8, v16, v17 offset1:1
	ds_write2_b32 v8, v18, v19 offset0:2 offset1:3
	ds_write2_b32 v9, v20, v21 offset1:1
	ds_write2_b32 v9, v22, v23 offset0:2 offset1:3
	ds_write2_b32 v10, v24, v25 offset1:1
	ds_write2_b32 v10, v26, v27 offset0:2 offset1:3
	ds_write2_b32 v11, v28, v29 offset1:1
	ds_write2_b32 v11, v30, v31 offset0:2 offset1:3
	v_and_b32_e32 v82, s27, v2
	v_xor_b32_e32 v82, s26, v82
	v_lshl_add_u32 v82, v82, 7, v14
	v_add_u32_e32 v83, 0x20000, v82
	s_waitcnt lgkmcnt(0)
	s_barrier
	ds_read2_b32 v[48:49], v12 offset1:65
	ds_read2_b32 v[50:51], v12 offset0:130 offset1:195
	ds_read2_b32 v[52:53], v13 offset1:65
	ds_read2_b32 v[54:55], v13 offset0:130 offset1:195
	ds_read2_b32 v[56:57], v12 offset0:32 offset1:97
	ds_read2_b32 v[58:59], v12 offset0:162 offset1:227
	ds_read2_b32 v[60:61], v13 offset0:32 offset1:97
	ds_read2_b32 v[62:63], v13 offset0:162 offset1:227
	s_waitcnt lgkmcnt(4)
	v_cvt_pk_bf16_f32 v64, v48, v49
	v_cvt_pk_bf16_f32 v65, v50, v51
	v_cvt_pk_bf16_f32 v66, v52, v53
	v_cvt_pk_bf16_f32 v67, v54, v55
	s_waitcnt lgkmcnt(0)
	v_cvt_pk_bf16_f32 v68, v56, v57
	v_cvt_pk_bf16_f32 v69, v58, v59
	v_cvt_pk_bf16_f32 v70, v60, v61
	v_cvt_pk_bf16_f32 v71, v62, v63
	global_store_dwordx4 v82, v[64:67], s[16:17] sc1
	global_store_dwordx4 v83, v[68:71], s[16:17] sc1
	s_mov_b64 s[16:17], s[14:15]
	s_mov_b32 s26, s6
	s_mov_b32 s27, s13
	s_mov_b32 s4, s18
	s_cmpk_lt_u32 s4, 0x2300
	s_cbranch_scc0 .Ltr_drain
	s_add_u32 s18, s4, s3
	s_cmpk_lt_u32 s18, 0x2300
	s_cselect_b32 s19, s18, s4
	s_mov_b32 s5, s19

.Ltr_b_end:
	v_mad_u32_u24 v4, v78, s12, v1
	v_mad_u32_u24 v5, v79, s12, v1
	v_mad_u32_u24 v6, v80, s12, v1
	v_mad_u32_u24 v7, v81, s12, v1
	global_load_dwordx4 v[16:19], v4, s[10:11]
	global_load_dwordx4 v[20:23], v5, s[10:11]
	global_load_dwordx4 v[24:27], v6, s[10:11]
	global_load_dwordx4 v[28:31], v7, s[10:11]
	s_waitcnt vmcnt(4)
	ds_write2_b32 v72, v32, v33 offset1:1
	ds_write2_b32 v72, v34, v35 offset0:2 offset1:3
	ds_write2_b32 v73, v36, v37 offset1:1
	ds_write2_b32 v73, v38, v39 offset0:2 offset1:3
	ds_write2_b32 v74, v40, v41 offset1:1
	ds_write2_b32 v74, v42, v43 offset0:2 offset1:3
	ds_write2_b32 v75, v44, v45 offset1:1
	ds_write2_b32 v75, v46, v47 offset0:2 offset1:3
	v_and_b32_e32 v82, s27, v2
	v_xor_b32_e32 v82, s26, v82
	v_lshl_add_u32 v82, v82, 7, v14
	v_add_u32_e32 v83, 0x20000, v82
	s_waitcnt lgkmcnt(0)
	s_barrier
	ds_read2_b32 v[48:49], v76 offset1:65
	ds_read2_b32 v[50:51], v76 offset0:130 offset1:195
	ds_read2_b32 v[52:53], v77 offset1:65
	ds_read2_b32 v[54:55], v77 offset0:130 offset1:195
	ds_read2_b32 v[56:57], v76 offset0:32 offset1:97
	ds_read2_b32 v[58:59], v76 offset0:162 offset1:227
	ds_read2_b32 v[60:61], v77 offset0:32 offset1:97
	ds_read2_b32 v[62:63], v77 offset0:162 offset1:227
	s_waitcnt lgkmcnt(4)
	v_cvt_pk_bf16_f32 v64, v48, v49
	v_cvt_pk_bf16_f32 v65, v50, v51
	v_cvt_pk_bf16_f32 v66, v52, v53
	v_cvt_pk_bf16_f32 v67, v54, v55
	s_waitcnt lgkmcnt(0)
	v_cvt_pk_bf16_f32 v68, v56, v57
	v_cvt_pk_bf16_f32 v69, v58, v59
	v_cvt_pk_bf16_f32 v70, v60, v61
	v_cvt_pk_bf16_f32 v71, v62, v63
	global_store_dwordx4 v82, v[64:67], s[16:17] sc1
	global_store_dwordx4 v83, v[68:71], s[16:17] sc1
	s_mov_b64 s[16:17], s[14:15]
	s_mov_b32 s26, s6
	s_mov_b32 s27, s13
	s_mov_b32 s4, s18
	s_cmpk_lt_u32 s4, 0x2300
	s_cbranch_scc0 .Ltr_drain
	s_branch .Ltr_loop

.Lp1m_kloop:
	s_waitcnt vmcnt(0) lgkmcnt(0)
	s_barrier
	ds_read_b128 v[170:173], v232 offset:24576
	ds_read_b128 v[174:177], v232 offset:26624
	ds_read_b128 v[178:181], v230 offset:24576
	ds_read_b128 v[182:185], v230 offset:26624
	ds_read_b128 v[186:189], v230 offset:28672
	ds_read_b128 v[190:193], v230 offset:30720
	s_setprio 1
	v_mfma_f32_32x32x16_bf16 v[48:63], v[222:225], v[206:209], v[48:63]
	v_mfma_f32_32x32x16_bf16 v[32:47], v[222:225], v[210:213], v[32:47]
	v_mfma_f32_32x32x16_bf16 v[16:31], v[226:229], v[206:209], v[16:31]
	v_mfma_f32_32x32x16_bf16 v[0:15], v[226:229], v[210:213], v[0:15]
	s_setprio 0
	s_add_u32 m0, s101, 0xc000
	s_nop 0
	global_load_lds_dwordx4 v234, s[98:99]
	s_add_u32 m0, s101, 0x0
	s_nop 0
	global_load_lds_dwordx4 v234, s[44:45]
	s_add_u32 m0, s101, 0xc400
	s_nop 0
	global_load_lds_dwordx4 v235, s[98:99]
	s_add_u32 m0, s101, 0x400
	s_nop 0
	global_load_lds_dwordx4 v235, s[44:45]
	s_waitcnt lgkmcnt(2)
	s_setprio 1
	v_mfma_f32_32x32x16_bf16 v[112:127], v[178:181], v[170:173], v[112:127]
	v_mfma_f32_32x32x16_bf16 v[96:111], v[178:181], v[174:177], v[96:111]
	v_mfma_f32_32x32x16_bf16 v[80:95], v[182:185], v[170:173], v[80:95]
	v_mfma_f32_32x32x16_bf16 v[64:79], v[182:185], v[174:177], v[64:79]
	s_setprio 0
	ds_read_b128 v[206:209], v233 offset:24576
	ds_read_b128 v[210:213], v233 offset:26624
	ds_read_b128 v[214:217], v231 offset:24576
	ds_read_b128 v[218:221], v231 offset:26624
	s_add_u32 m0, s101, 0xc800
	s_nop 0
	global_load_lds_dwordx4 v236, s[98:99]
	s_add_u32 m0, s101, 0x800
	s_nop 0
	global_load_lds_dwordx4 v236, s[44:45]
	s_add_u32 m0, s101, 0xcc00
	s_nop 0
	global_load_lds_dwordx4 v237, s[98:99]
	s_add_u32 m0, s101, 0xc00
	s_nop 0
	global_load_lds_dwordx4 v237, s[44:45]
	s_waitcnt lgkmcnt(4)
	s_setprio 1
	v_mfma_f32_32x32x16_bf16 v[48:63], v[186:189], v[170:173], v[48:63]
	v_mfma_f32_32x32x16_bf16 v[32:47], v[186:189], v[174:177], v[32:47]
	v_mfma_f32_32x32x16_bf16 v[16:31], v[190:193], v[170:173], v[16:31]
	v_mfma_f32_32x32x16_bf16 v[0:15], v[190:193], v[174:177], v[0:15]
	s_setprio 0
	ds_read_b128 v[222:225], v231 offset:28672
	ds_read_b128 v[226:229], v231 offset:30720
	v_xad_u32 v241, s36, v240, v238
	v_xad_u32 v242, s37, v240, v239
	s_add_u32 m0, s49, 0xc000
	s_nop 0
	global_load_lds_dwordx4 v241, s[94:95]
	s_add_u32 m0, s49, 0xffffffc0
	s_nop 0
	global_load_lds_dwordx4 v241, s[94:95] offset:64
	s_add_u32 m0, s49, 0xc400
	s_nop 0
	global_load_lds_dwordx4 v242, s[94:95]
	s_add_u32 m0, s49, 0x3c0
	s_nop 0
	global_load_lds_dwordx4 v242, s[94:95] offset:64
	s_add_u32 s36, s36, 0x80
	s_xor_b32 s37, s36, 0x800
	s_add_u32 s98, s98, 128
	s_addc_u32 s99, s99, 0
	s_add_u32 s44, s44, 128
	s_addc_u32 s45, s45, 0
	s_waitcnt lgkmcnt(2)
	s_setprio 1
	v_mfma_f32_32x32x16_bf16 v[112:127], v[214:217], v[206:209], v[112:127]
	v_mfma_f32_32x32x16_bf16 v[96:111], v[214:217], v[210:213], v[96:111]
	v_mfma_f32_32x32x16_bf16 v[80:95], v[218:221], v[206:209], v[80:95]
	v_mfma_f32_32x32x16_bf16 v[64:79], v[218:221], v[210:213], v[64:79]
	s_setprio 0
	s_waitcnt vmcnt(0) lgkmcnt(0)
	s_barrier
	ds_read_b128 v[170:173], v232 offset:49152
	ds_read_b128 v[174:177], v232 offset:51200
	ds_read_b128 v[178:181], v230 offset:49152
	ds_read_b128 v[182:185], v230 offset:51200
	ds_read_b128 v[186:189], v230 offset:53248
	ds_read_b128 v[190:193], v230 offset:55296
	s_setprio 1
	v_mfma_f32_32x32x16_bf16 v[48:63], v[222:225], v[206:209], v[48:63]
	v_mfma_f32_32x32x16_bf16 v[32:47], v[222:225], v[210:213], v[32:47]
	v_mfma_f32_32x32x16_bf16 v[16:31], v[226:229], v[206:209], v[16:31]
	v_mfma_f32_32x32x16_bf16 v[0:15], v[226:229], v[210:213], v[0:15]
	s_setprio 0
	s_waitcnt lgkmcnt(2)
	s_setprio 1
	v_mfma_f32_32x32x16_bf16 v[112:127], v[178:181], v[170:173], v[112:127]
	v_mfma_f32_32x32x16_bf16 v[96:111], v[178:181], v[174:177], v[96:111]
	v_mfma_f32_32x32x16_bf16 v[80:95], v[182:185], v[170:173], v[80:95]
	v_mfma_f32_32x32x16_bf16 v[64:79], v[182:185], v[174:177], v[64:79]
	s_setprio 0
	ds_read_b128 v[206:209], v233 offset:49152
	ds_read_b128 v[210:213], v233 offset:51200
	ds_read_b128 v[214:217], v231 offset:49152
	ds_read_b128 v[218:221], v231 offset:51200
	s_waitcnt lgkmcnt(4)
	s_setprio 1
	v_mfma_f32_32x32x16_bf16 v[48:63], v[186:189], v[170:173], v[48:63]
	v_mfma_f32_32x32x16_bf16 v[32:47], v[186:189], v[174:177], v[32:47]
	v_mfma_f32_32x32x16_bf16 v[16:31], v[190:193], v[170:173], v[16:31]
	v_mfma_f32_32x32x16_bf16 v[0:15], v[190:193], v[174:177], v[0:15]
	s_setprio 0
	ds_read_b128 v[222:225], v231 offset:53248
	ds_read_b128 v[226:229], v231 offset:55296
	s_waitcnt lgkmcnt(2)
	s_setprio 1
	v_mfma_f32_32x32x16_bf16 v[112:127], v[214:217], v[206:209], v[112:127]
	v_mfma_f32_32x32x16_bf16 v[96:111], v[214:217], v[210:213], v[96:111]
	v_mfma_f32_32x32x16_bf16 v[80:95], v[218:221], v[206:209], v[80:95]
	v_mfma_f32_32x32x16_bf16 v[64:79], v[218:221], v[210:213], v[64:79]
	s_setprio 0
	s_waitcnt vmcnt(0) lgkmcnt(0)
	s_barrier
	ds_read_b128 v[170:173], v232 offset:0
	ds_read_b128 v[174:177], v232 offset:2048
	ds_read_b128 v[178:181], v230 offset:0
	ds_read_b128 v[182:185], v230 offset:2048
	ds_read_b128 v[186:189], v230 offset:4096
	ds_read_b128 v[190:193], v230 offset:6144
	s_setprio 1
	v_mfma_f32_32x32x16_bf16 v[48:63], v[222:225], v[206:209], v[48:63]
	v_mfma_f32_32x32x16_bf16 v[32:47], v[222:225], v[210:213], v[32:47]
	v_mfma_f32_32x32x16_bf16 v[16:31], v[226:229], v[206:209], v[16:31]
	v_mfma_f32_32x32x16_bf16 v[0:15], v[226:229], v[210:213], v[0:15]
	s_setprio 0
	s_add_u32 m0, s101, 0x6000
	s_nop 0
	global_load_lds_dwordx4 v234, s[98:99]
	s_add_u32 m0, s101, 0xc000
	s_nop 0
	global_load_lds_dwordx4 v234, s[44:45]
	s_add_u32 m0, s101, 0x6400
	s_nop 0
	global_load_lds_dwordx4 v235, s[98:99]
	s_add_u32 m0, s101, 0xc400
	s_nop 0
	global_load_lds_dwordx4 v235, s[44:45]
	s_waitcnt lgkmcnt(2)
	s_setprio 1
	v_mfma_f32_32x32x16_bf16 v[112:127], v[178:181], v[170:173], v[112:127]
	v_mfma_f32_32x32x16_bf16 v[96:111], v[178:181], v[174:177], v[96:111]
	v_mfma_f32_32x32x16_bf16 v[80:95], v[182:185], v[170:173], v[80:95]
	v_mfma_f32_32x32x16_bf16 v[64:79], v[182:185], v[174:177], v[64:79]
	s_setprio 0
	ds_read_b128 v[206:209], v233 offset:0
	ds_read_b128 v[210:213], v233 offset:2048
	ds_read_b128 v[214:217], v231 offset:0
	ds_read_b128 v[218:221], v231 offset:2048
	s_add_u32 m0, s101, 0x6800
	s_nop 0
	global_load_lds_dwordx4 v236, s[98:99]
	s_add_u32 m0, s101, 0xc800
	s_nop 0
	global_load_lds_dwordx4 v236, s[44:45]
	s_add_u32 m0, s101, 0x6c00
	s_nop 0
	global_load_lds_dwordx4 v237, s[98:99]
	s_add_u32 m0, s101, 0xcc00
	s_nop 0
	global_load_lds_dwordx4 v237, s[44:45]
	s_waitcnt lgkmcnt(4)
	s_setprio 1
	v_mfma_f32_32x32x16_bf16 v[48:63], v[186:189], v[170:173], v[48:63]
	v_mfma_f32_32x32x16_bf16 v[32:47], v[186:189], v[174:177], v[32:47]
	v_mfma_f32_32x32x16_bf16 v[16:31], v[190:193], v[170:173], v[16:31]
	v_mfma_f32_32x32x16_bf16 v[0:15], v[190:193], v[174:177], v[0:15]
	s_setprio 0
	ds_read_b128 v[222:225], v231 offset:4096
	ds_read_b128 v[226:229], v231 offset:6144
	v_xad_u32 v241, s36, v240, v238
	v_xad_u32 v242, s37, v240, v239
	s_add_u32 m0, s49, 0x6000
	s_nop 0
	global_load_lds_dwordx4 v241, s[94:95]
	s_add_u32 m0, s49, 0xbfc0
	s_nop 0
	global_load_lds_dwordx4 v241, s[94:95] offset:64
	s_add_u32 m0, s49, 0x6400
	s_nop 0
	global_load_lds_dwordx4 v242, s[94:95]
	s_add_u32 m0, s49, 0xc3c0
	s_nop 0
	global_load_lds_dwordx4 v242, s[94:95] offset:64
	s_add_u32 s36, s36, 0x80
	s_xor_b32 s37, s36, 0x800
	s_add_u32 s98, s98, 128
	s_addc_u32 s99, s99, 0
	s_add_u32 s44, s44, 128
	s_addc_u32 s45, s45, 0
	s_waitcnt lgkmcnt(2)
	s_setprio 1
	v_mfma_f32_32x32x16_bf16 v[112:127], v[214:217], v[206:209], v[112:127]
	v_mfma_f32_32x32x16_bf16 v[96:111], v[214:217], v[210:213], v[96:111]
	v_mfma_f32_32x32x16_bf16 v[80:95], v[218:221], v[206:209], v[80:95]
	v_mfma_f32_32x32x16_bf16 v[64:79], v[218:221], v[210:213], v[64:79]
	s_setprio 0
	s_waitcnt vmcnt(0) lgkmcnt(0)
	s_barrier
	ds_read_b128 v[170:173], v232 offset:24576
	ds_read_b128 v[174:177], v232 offset:26624
	ds_read_b128 v[178:181], v230 offset:24576
	ds_read_b128 v[182:185], v230 offset:26624
	ds_read_b128 v[186:189], v230 offset:28672
	ds_read_b128 v[190:193], v230 offset:30720
	s_setprio 1
	v_mfma_f32_32x32x16_bf16 v[48:63], v[222:225], v[206:209], v[48:63]
	v_mfma_f32_32x32x16_bf16 v[32:47], v[222:225], v[210:213], v[32:47]
	v_mfma_f32_32x32x16_bf16 v[16:31], v[226:229], v[206:209], v[16:31]
	v_mfma_f32_32x32x16_bf16 v[0:15], v[226:229], v[210:213], v[0:15]
	s_setprio 0
	s_waitcnt lgkmcnt(2)
	s_setprio 1
	v_mfma_f32_32x32x16_bf16 v[112:127], v[178:181], v[170:173], v[112:127]
	v_mfma_f32_32x32x16_bf16 v[96:111], v[178:181], v[174:177], v[96:111]
	v_mfma_f32_32x32x16_bf16 v[80:95], v[182:185], v[170:173], v[80:95]
	v_mfma_f32_32x32x16_bf16 v[64:79], v[182:185], v[174:177], v[64:79]
	s_setprio 0
	ds_read_b128 v[206:209], v233 offset:24576
	ds_read_b128 v[210:213], v233 offset:26624
	ds_read_b128 v[214:217], v231 offset:24576
	ds_read_b128 v[218:221], v231 offset:26624
	s_waitcnt lgkmcnt(4)
	s_setprio 1
	v_mfma_f32_32x32x16_bf16 v[48:63], v[186:189], v[170:173], v[48:63]
	v_mfma_f32_32x32x16_bf16 v[32:47], v[186:189], v[174:177], v[32:47]
	v_mfma_f32_32x32x16_bf16 v[16:31], v[190:193], v[170:173], v[16:31]
	v_mfma_f32_32x32x16_bf16 v[0:15], v[190:193], v[174:177], v[0:15]
	s_setprio 0
	ds_read_b128 v[222:225], v231 offset:28672
	ds_read_b128 v[226:229], v231 offset:30720
	s_waitcnt lgkmcnt(2)
	s_setprio 1
	v_mfma_f32_32x32x16_bf16 v[112:127], v[214:217], v[206:209], v[112:127]
	v_mfma_f32_32x32x16_bf16 v[96:111], v[214:217], v[210:213], v[96:111]
	v_mfma_f32_32x32x16_bf16 v[80:95], v[218:221], v[206:209], v[80:95]
	v_mfma_f32_32x32x16_bf16 v[64:79], v[218:221], v[210:213], v[64:79]
	s_setprio 0
	s_waitcnt vmcnt(0) lgkmcnt(0)
	s_barrier
	ds_read_b128 v[170:173], v232 offset:49152
	ds_read_b128 v[174:177], v232 offset:51200
	ds_read_b128 v[178:181], v230 offset:49152
	ds_read_b128 v[182:185], v230 offset:51200
	ds_read_b128 v[186:189], v230 offset:53248
	ds_read_b128 v[190:193], v230 offset:55296
	s_setprio 1
	v_mfma_f32_32x32x16_bf16 v[48:63], v[222:225], v[206:209], v[48:63]
	v_mfma_f32_32x32x16_bf16 v[32:47], v[222:225], v[210:213], v[32:47]
	v_mfma_f32_32x32x16_bf16 v[16:31], v[226:229], v[206:209], v[16:31]
	v_mfma_f32_32x32x16_bf16 v[0:15], v[226:229], v[210:213], v[0:15]
	s_setprio 0
	s_add_u32 m0, s101, 0x0
	s_nop 0
	global_load_lds_dwordx4 v234, s[98:99]
	s_add_u32 m0, s101, 0x6000
	s_nop 0
	global_load_lds_dwordx4 v234, s[44:45]
	s_add_u32 m0, s101, 0x400
	s_nop 0
	global_load_lds_dwordx4 v235, s[98:99]
	s_add_u32 m0, s101, 0x6400
	s_nop 0
	global_load_lds_dwordx4 v235, s[44:45]
	s_waitcnt lgkmcnt(2)
	s_setprio 1
	v_mfma_f32_32x32x16_bf16 v[112:127], v[178:181], v[170:173], v[112:127]
	v_mfma_f32_32x32x16_bf16 v[96:111], v[178:181], v[174:177], v[96:111]
	v_mfma_f32_32x32x16_bf16 v[80:95], v[182:185], v[170:173], v[80:95]
	v_mfma_f32_32x32x16_bf16 v[64:79], v[182:185], v[174:177], v[64:79]
	s_setprio 0
	ds_read_b128 v[206:209], v233 offset:49152
	ds_read_b128 v[210:213], v233 offset:51200
	ds_read_b128 v[214:217], v231 offset:49152
	ds_read_b128 v[218:221], v231 offset:51200
	s_add_u32 m0, s101, 0x800
	s_nop 0
	global_load_lds_dwordx4 v236, s[98:99]
	s_add_u32 m0, s101, 0x6800
	s_nop 0
	global_load_lds_dwordx4 v236, s[44:45]
	s_add_u32 m0, s101, 0xc00
	s_nop 0
	global_load_lds_dwordx4 v237, s[98:99]
	s_add_u32 m0, s101, 0x6c00
	s_nop 0
	global_load_lds_dwordx4 v237, s[44:45]
	s_waitcnt lgkmcnt(4)
	s_setprio 1
	v_mfma_f32_32x32x16_bf16 v[48:63], v[186:189], v[170:173], v[48:63]
	v_mfma_f32_32x32x16_bf16 v[32:47], v[186:189], v[174:177], v[32:47]
	v_mfma_f32_32x32x16_bf16 v[16:31], v[190:193], v[170:173], v[16:31]
	v_mfma_f32_32x32x16_bf16 v[0:15], v[190:193], v[174:177], v[0:15]
	s_setprio 0
	ds_read_b128 v[222:225], v231 offset:53248
	ds_read_b128 v[226:229], v231 offset:55296
	v_xad_u32 v241, s36, v240, v238
	v_xad_u32 v242, s37, v240, v239
	s_add_u32 m0, s49, 0x0
	s_nop 0
	global_load_lds_dwordx4 v241, s[94:95]
	s_add_u32 m0, s49, 0x5fc0
	s_nop 0
	global_load_lds_dwordx4 v241, s[94:95] offset:64
	s_add_u32 m0, s49, 0x400
	s_nop 0
	global_load_lds_dwordx4 v242, s[94:95]
	s_add_u32 m0, s49, 0x63c0
	s_nop 0
	global_load_lds_dwordx4 v242, s[94:95] offset:64
	s_add_u32 s36, s36, 0x80
	s_xor_b32 s37, s36, 0x800
	s_add_u32 s98, s98, 128
	s_addc_u32 s99, s99, 0
	s_add_u32 s44, s44, 128
	s_addc_u32 s45, s45, 0
	s_waitcnt lgkmcnt(2)
	s_setprio 1
	v_mfma_f32_32x32x16_bf16 v[112:127], v[214:217], v[206:209], v[112:127]
	v_mfma_f32_32x32x16_bf16 v[96:111], v[214:217], v[210:213], v[96:111]
	v_mfma_f32_32x32x16_bf16 v[80:95], v[218:221], v[206:209], v[80:95]
	v_mfma_f32_32x32x16_bf16 v[64:79], v[218:221], v[210:213], v[64:79]
	s_setprio 0
	s_waitcnt vmcnt(0) lgkmcnt(0)
	s_barrier
	ds_read_b128 v[170:173], v232 offset:0
	ds_read_b128 v[174:177], v232 offset:2048
	ds_read_b128 v[178:181], v230 offset:0
	ds_read_b128 v[182:185], v230 offset:2048
	ds_read_b128 v[186:189], v230 offset:4096
	ds_read_b128 v[190:193], v230 offset:6144
	s_setprio 1
	v_mfma_f32_32x32x16_bf16 v[48:63], v[222:225], v[206:209], v[48:63]
	v_mfma_f32_32x32x16_bf16 v[32:47], v[222:225], v[210:213], v[32:47]
	v_mfma_f32_32x32x16_bf16 v[16:31], v[226:229], v[206:209], v[16:31]
	v_mfma_f32_32x32x16_bf16 v[0:15], v[226:229], v[210:213], v[0:15]
	s_setprio 0
	s_waitcnt lgkmcnt(2)
	s_setprio 1
	v_mfma_f32_32x32x16_bf16 v[112:127], v[178:181], v[170:173], v[112:127]
	v_mfma_f32_32x32x16_bf16 v[96:111], v[178:181], v[174:177], v[96:111]
	v_mfma_f32_32x32x16_bf16 v[80:95], v[182:185], v[170:173], v[80:95]
	v_mfma_f32_32x32x16_bf16 v[64:79], v[182:185], v[174:177], v[64:79]
	s_setprio 0
	ds_read_b128 v[206:209], v233 offset:0
	ds_read_b128 v[210:213], v233 offset:2048
	ds_read_b128 v[214:217], v231 offset:0
	ds_read_b128 v[218:221], v231 offset:2048
	s_waitcnt lgkmcnt(4)
	s_setprio 1
	v_mfma_f32_32x32x16_bf16 v[48:63], v[186:189], v[170:173], v[48:63]
	v_mfma_f32_32x32x16_bf16 v[32:47], v[186:189], v[174:177], v[32:47]
	v_mfma_f32_32x32x16_bf16 v[16:31], v[190:193], v[170:173], v[16:31]
	v_mfma_f32_32x32x16_bf16 v[0:15], v[190:193], v[174:177], v[0:15]
	s_setprio 0
	ds_read_b128 v[222:225], v231 offset:4096
	ds_read_b128 v[226:229], v231 offset:6144
	s_waitcnt lgkmcnt(2)
	s_setprio 1
	v_mfma_f32_32x32x16_bf16 v[112:127], v[214:217], v[206:209], v[112:127]
	v_mfma_f32_32x32x16_bf16 v[96:111], v[214:217], v[210:213], v[96:111]
	v_mfma_f32_32x32x16_bf16 v[80:95], v[218:221], v[206:209], v[80:95]
	v_mfma_f32_32x32x16_bf16 v[64:79], v[218:221], v[210:213], v[64:79]
	s_setprio 0
	s_sub_u32 s100, s100, 1
	s_cmp_lg_u32 s100, 0
	s_cbranch_scc1 .Lp1m_kloop
	s_waitcnt vmcnt(0) lgkmcnt(0)
	s_barrier
	ds_read_b128 v[170:173], v232 offset:24576
	ds_read_b128 v[174:177], v232 offset:26624
	ds_read_b128 v[178:181], v230 offset:24576
	ds_read_b128 v[182:185], v230 offset:26624
	ds_read_b128 v[186:189], v230 offset:28672
	ds_read_b128 v[190:193], v230 offset:30720
	s_setprio 1
	v_mfma_f32_32x32x16_bf16 v[48:63], v[222:225], v[206:209], v[48:63]
	v_mfma_f32_32x32x16_bf16 v[32:47], v[222:225], v[210:213], v[32:47]
	v_mfma_f32_32x32x16_bf16 v[16:31], v[226:229], v[206:209], v[16:31]
	v_mfma_f32_32x32x16_bf16 v[0:15], v[226:229], v[210:213], v[0:15]
	s_setprio 0
	s_add_u32 m0, s101, 0xc000
	s_nop 0
	global_load_lds_dwordx4 v234, s[98:99]
	s_add_u32 m0, s101, 0x0
	s_nop 0
	global_load_lds_dwordx4 v234, s[44:45]
	s_add_u32 m0, s101, 0xc400
	s_nop 0
	global_load_lds_dwordx4 v235, s[98:99]
	s_add_u32 m0, s101, 0x400
	s_nop 0
	global_load_lds_dwordx4 v235, s[44:45]
	s_waitcnt lgkmcnt(2)
	s_setprio 1
	v_mfma_f32_32x32x16_bf16 v[112:127], v[178:181], v[170:173], v[112:127]
	v_mfma_f32_32x32x16_bf16 v[96:111], v[178:181], v[174:177], v[96:111]
	v_mfma_f32_32x32x16_bf16 v[80:95], v[182:185], v[170:173], v[80:95]
	v_mfma_f32_32x32x16_bf16 v[64:79], v[182:185], v[174:177], v[64:79]
	s_setprio 0
	ds_read_b128 v[206:209], v233 offset:24576
	ds_read_b128 v[210:213], v233 offset:26624
	ds_read_b128 v[214:217], v231 offset:24576
	ds_read_b128 v[218:221], v231 offset:26624
	s_add_u32 m0, s101, 0xc800
	s_nop 0
	global_load_lds_dwordx4 v236, s[98:99]
	s_add_u32 m0, s101, 0x800
	s_nop 0
	global_load_lds_dwordx4 v236, s[44:45]
	s_add_u32 m0, s101, 0xcc00
	s_nop 0
	global_load_lds_dwordx4 v237, s[98:99]
	s_add_u32 m0, s101, 0xc00
	s_nop 0
	global_load_lds_dwordx4 v237, s[44:45]
	s_waitcnt lgkmcnt(4)
	s_setprio 1
	v_mfma_f32_32x32x16_bf16 v[48:63], v[186:189], v[170:173], v[48:63]
	v_mfma_f32_32x32x16_bf16 v[32:47], v[186:189], v[174:177], v[32:47]
	v_mfma_f32_32x32x16_bf16 v[16:31], v[190:193], v[170:173], v[16:31]
	v_mfma_f32_32x32x16_bf16 v[0:15], v[190:193], v[174:177], v[0:15]
	s_setprio 0
	ds_read_b128 v[222:225], v231 offset:28672
	ds_read_b128 v[226:229], v231 offset:30720
	v_xad_u32 v241, s36, v240, v238
	v_xad_u32 v242, s37, v240, v239
	s_add_u32 m0, s49, 0xc000
	s_nop 0
	global_load_lds_dwordx4 v241, s[94:95]
	s_add_u32 m0, s49, 0xffffffc0
	s_nop 0
	global_load_lds_dwordx4 v241, s[94:95] offset:64
	s_add_u32 m0, s49, 0xc400
	s_nop 0
	global_load_lds_dwordx4 v242, s[94:95]
	s_add_u32 m0, s49, 0x3c0
	s_nop 0
	global_load_lds_dwordx4 v242, s[94:95] offset:64
	s_add_u32 s36, s36, 0x80
	s_xor_b32 s37, s36, 0x800
	s_add_u32 s98, s98, 128
	s_addc_u32 s99, s99, 0
	s_add_u32 s44, s44, 128
	s_addc_u32 s45, s45, 0
	s_waitcnt lgkmcnt(2)
	s_setprio 1
	v_mfma_f32_32x32x16_bf16 v[112:127], v[214:217], v[206:209], v[112:127]
	v_mfma_f32_32x32x16_bf16 v[96:111], v[214:217], v[210:213], v[96:111]
	v_mfma_f32_32x32x16_bf16 v[80:95], v[218:221], v[206:209], v[80:95]
	v_mfma_f32_32x32x16_bf16 v[64:79], v[218:221], v[210:213], v[64:79]
	s_setprio 0
	s_waitcnt vmcnt(0) lgkmcnt(0)
	s_barrier
	ds_read_b128 v[170:173], v232 offset:49152
	ds_read_b128 v[174:177], v232 offset:51200
	ds_read_b128 v[178:181], v230 offset:49152
	ds_read_b128 v[182:185], v230 offset:51200
	ds_read_b128 v[186:189], v230 offset:53248
	ds_read_b128 v[190:193], v230 offset:55296
	s_setprio 1
	v_mfma_f32_32x32x16_bf16 v[48:63], v[222:225], v[206:209], v[48:63]
	v_mfma_f32_32x32x16_bf16 v[32:47], v[222:225], v[210:213], v[32:47]
	v_mfma_f32_32x32x16_bf16 v[16:31], v[226:229], v[206:209], v[16:31]
	v_mfma_f32_32x32x16_bf16 v[0:15], v[226:229], v[210:213], v[0:15]
	s_setprio 0
	s_waitcnt lgkmcnt(2)
	s_setprio 1
	v_mfma_f32_32x32x16_bf16 v[112:127], v[178:181], v[170:173], v[112:127]
	v_mfma_f32_32x32x16_bf16 v[96:111], v[178:181], v[174:177], v[96:111]
	v_mfma_f32_32x32x16_bf16 v[80:95], v[182:185], v[170:173], v[80:95]
	v_mfma_f32_32x32x16_bf16 v[64:79], v[182:185], v[174:177], v[64:79]
	s_setprio 0
	ds_read_b128 v[206:209], v233 offset:49152
	ds_read_b128 v[210:213], v233 offset:51200
	ds_read_b128 v[214:217], v231 offset:49152
	ds_read_b128 v[218:221], v231 offset:51200
	s_waitcnt lgkmcnt(4)
	s_setprio 1
	v_mfma_f32_32x32x16_bf16 v[48:63], v[186:189], v[170:173], v[48:63]
	v_mfma_f32_32x32x16_bf16 v[32:47], v[186:189], v[174:177], v[32:47]
	v_mfma_f32_32x32x16_bf16 v[16:31], v[190:193], v[170:173], v[16:31]
	v_mfma_f32_32x32x16_bf16 v[0:15], v[190:193], v[174:177], v[0:15]
	s_setprio 0
	ds_read_b128 v[222:225], v231 offset:53248
	ds_read_b128 v[226:229], v231 offset:55296
	s_waitcnt lgkmcnt(2)
	s_setprio 1
	v_mfma_f32_32x32x16_bf16 v[112:127], v[214:217], v[206:209], v[112:127]
	v_mfma_f32_32x32x16_bf16 v[96:111], v[214:217], v[210:213], v[96:111]
	v_mfma_f32_32x32x16_bf16 v[80:95], v[218:221], v[206:209], v[80:95]
	v_mfma_f32_32x32x16_bf16 v[64:79], v[218:221], v[210:213], v[64:79]
	s_setprio 0
	s_waitcnt vmcnt(0) lgkmcnt(0)
	s_barrier
	ds_read_b128 v[170:173], v232 offset:0
	ds_read_b128 v[174:177], v232 offset:2048
	ds_read_b128 v[178:181], v230 offset:0
	ds_read_b128 v[182:185], v230 offset:2048
	ds_read_b128 v[186:189], v230 offset:4096
	ds_read_b128 v[190:193], v230 offset:6144
	s_setprio 1
	v_mfma_f32_32x32x16_bf16 v[48:63], v[222:225], v[206:209], v[48:63]
	v_mfma_f32_32x32x16_bf16 v[32:47], v[222:225], v[210:213], v[32:47]
	v_mfma_f32_32x32x16_bf16 v[16:31], v[226:229], v[206:209], v[16:31]
	v_mfma_f32_32x32x16_bf16 v[0:15], v[226:229], v[210:213], v[0:15]
	s_setprio 0
	s_waitcnt lgkmcnt(2)
	s_setprio 1
	v_mfma_f32_32x32x16_bf16 v[112:127], v[178:181], v[170:173], v[112:127]
	v_mfma_f32_32x32x16_bf16 v[96:111], v[178:181], v[174:177], v[96:111]
	v_mfma_f32_32x32x16_bf16 v[80:95], v[182:185], v[170:173], v[80:95]
	v_mfma_f32_32x32x16_bf16 v[64:79], v[182:185], v[174:177], v[64:79]
	s_setprio 0
	ds_read_b128 v[206:209], v233 offset:0
	ds_read_b128 v[210:213], v233 offset:2048
	ds_read_b128 v[214:217], v231 offset:0
	ds_read_b128 v[218:221], v231 offset:2048
	s_waitcnt lgkmcnt(4)
	s_setprio 1
	v_mfma_f32_32x32x16_bf16 v[48:63], v[186:189], v[170:173], v[48:63]
	v_mfma_f32_32x32x16_bf16 v[32:47], v[186:189], v[174:177], v[32:47]
	v_mfma_f32_32x32x16_bf16 v[16:31], v[190:193], v[170:173], v[16:31]
	v_mfma_f32_32x32x16_bf16 v[0:15], v[190:193], v[174:177], v[0:15]
	s_setprio 0
	ds_read_b128 v[222:225], v231 offset:4096
	ds_read_b128 v[226:229], v231 offset:6144
	s_waitcnt lgkmcnt(2)
	s_setprio 1
	v_mfma_f32_32x32x16_bf16 v[112:127], v[214:217], v[206:209], v[112:127]
	v_mfma_f32_32x32x16_bf16 v[96:111], v[214:217], v[210:213], v[96:111]
	v_mfma_f32_32x32x16_bf16 v[80:95], v[218:221], v[206:209], v[80:95]
	v_mfma_f32_32x32x16_bf16 v[64:79], v[218:221], v[210:213], v[64:79]
	s_setprio 0
	s_waitcnt lgkmcnt(0)
	s_setprio 1
	v_mfma_f32_32x32x16_bf16 v[48:63], v[222:225], v[206:209], v[48:63]
	v_mfma_f32_32x32x16_bf16 v[32:47], v[222:225], v[210:213], v[32:47]
	v_mfma_f32_32x32x16_bf16 v[16:31], v[226:229], v[206:209], v[16:31]
	v_mfma_f32_32x32x16_bf16 v[0:15], v[226:229], v[210:213], v[0:15]
	s_setprio 0
	s_mul_hi_i32 s41, s42, 0x540000
	s_mul_i32 s42, s42, 0x540000
	s_add_u32 s42, s31, s42
	s_addc_u32 s43, s33, s41
	s_lshl_b32 s40, s40, 8
	s_add_u32 s42, s42, s40
	s_addc_u32 s43, s43, 0
	s_add_i32 s16, s16, s17
	s_add_i32 s47, s47, s17
	v_lshrrev_b32_e32 v170, 6, v204
	v_and_b32_e32 v171, 31, v204
	v_bfe_u32 v172, v204, 5, 1
	v_mul_u32_u24_e32 v173, 0x4400, v170
	v_mul_u32_u24_e32 v174, 544, v172
	v_lshl_add_u32 v174, v171, 2, v174
	v_add3_u32 v174, v174, v173, 32
	v_and_b32_e32 v175, 7, v204
	v_bfe_u32 v176, v204, 3, 3
	v_mul_u32_u24_e32 v177, 272, v176
	v_lshl_add_u32 v177, v175, 5, v177
	v_add3_u32 v177, v177, v173, 32
	v_lshrrev_b32_e32 v178, 1, v170
	v_and_b32_e32 v179, 1, v170
	v_lshlrev_b32_e32 v178, 7, v178
	v_lshl_add_u32 v178, v176, 1, v178
	v_mul_u32_u24_e32 v178, 0x5400, v178
	v_lshl_add_u32 v178, v179, 7, v178
	v_lshl_add_u32 v178, v175, 4, v178
	v_add_u32_e32 v179, 0x5400, v178
	v_mov_b32_e32 v180, 0x05040100
	v_mov_b32_e32 v181, 0x07060302
	s_waitcnt vmcnt(0)
	s_barrier
	v_cvt_pk_bf16_f32 v112, v112, v113
	ds_write_b32 v174, v112 offset:0
	v_cvt_pk_bf16_f32 v114, v114, v115
	ds_write_b32 v174, v114 offset:272
	v_cvt_pk_bf16_f32 v116, v116, v117
	ds_write_b32 v174, v116 offset:1088
	v_cvt_pk_bf16_f32 v118, v118, v119
	ds_write_b32 v174, v118 offset:1360
	v_cvt_pk_bf16_f32 v120, v120, v121
	ds_write_b32 v174, v120 offset:2176
	v_cvt_pk_bf16_f32 v122, v122, v123
	ds_write_b32 v174, v122 offset:2448
	v_cvt_pk_bf16_f32 v124, v124, v125
	ds_write_b32 v174, v124 offset:3264
	v_cvt_pk_bf16_f32 v126, v126, v127
	ds_write_b32 v174, v126 offset:3536
	v_cvt_pk_bf16_f32 v96, v96, v97
	ds_write_b32 v174, v96 offset:128
	v_cvt_pk_bf16_f32 v98, v98, v99
	ds_write_b32 v174, v98 offset:400
	v_cvt_pk_bf16_f32 v100, v100, v101
	ds_write_b32 v174, v100 offset:1216
	v_cvt_pk_bf16_f32 v102, v102, v103
	ds_write_b32 v174, v102 offset:1488
	v_cvt_pk_bf16_f32 v104, v104, v105
	ds_write_b32 v174, v104 offset:2304
	v_cvt_pk_bf16_f32 v106, v106, v107
	ds_write_b32 v174, v106 offset:2576
	v_cvt_pk_bf16_f32 v108, v108, v109
	ds_write_b32 v174, v108 offset:3392
	v_cvt_pk_bf16_f32 v110, v110, v111
	ds_write_b32 v174, v110 offset:3664
	v_cvt_pk_bf16_f32 v80, v80, v81
	ds_write_b32 v174, v80 offset:4352
	v_cvt_pk_bf16_f32 v82, v82, v83
	ds_write_b32 v174, v82 offset:4624
	v_cvt_pk_bf16_f32 v84, v84, v85
	ds_write_b32 v174, v84 offset:5440
	v_cvt_pk_bf16_f32 v86, v86, v87
	ds_write_b32 v174, v86 offset:5712
	v_cvt_pk_bf16_f32 v88, v88, v89
	ds_write_b32 v174, v88 offset:6528
	v_cvt_pk_bf16_f32 v90, v90, v91
	ds_write_b32 v174, v90 offset:6800
	v_cvt_pk_bf16_f32 v92, v92, v93
	ds_write_b32 v174, v92 offset:7616
	v_cvt_pk_bf16_f32 v94, v94, v95
	ds_write_b32 v174, v94 offset:7888
	v_cvt_pk_bf16_f32 v64, v64, v65
	ds_write_b32 v174, v64 offset:4480
	v_cvt_pk_bf16_f32 v66, v66, v67
	ds_write_b32 v174, v66 offset:4752
	v_cvt_pk_bf16_f32 v68, v68, v69
	ds_write_b32 v174, v68 offset:5568
	v_cvt_pk_bf16_f32 v70, v70, v71
	ds_write_b32 v174, v70 offset:5840
	v_cvt_pk_bf16_f32 v72, v72, v73
	ds_write_b32 v174, v72 offset:6656
	v_cvt_pk_bf16_f32 v74, v74, v75
	ds_write_b32 v174, v74 offset:6928
	v_cvt_pk_bf16_f32 v76, v76, v77
	ds_write_b32 v174, v76 offset:7744
	v_cvt_pk_bf16_f32 v78, v78, v79
	ds_write_b32 v174, v78 offset:8016
	v_cvt_pk_bf16_f32 v48, v48, v49
	ds_write_b32 v174, v48 offset:8704
	v_cvt_pk_bf16_f32 v50, v50, v51
	ds_write_b32 v174, v50 offset:8976
	v_cvt_pk_bf16_f32 v52, v52, v53
	ds_write_b32 v174, v52 offset:9792
	v_cvt_pk_bf16_f32 v54, v54, v55
	ds_write_b32 v174, v54 offset:10064
	v_cvt_pk_bf16_f32 v56, v56, v57
	ds_write_b32 v174, v56 offset:10880
	v_cvt_pk_bf16_f32 v58, v58, v59
	ds_write_b32 v174, v58 offset:11152
	v_cvt_pk_bf16_f32 v60, v60, v61
	ds_write_b32 v174, v60 offset:11968
	v_cvt_pk_bf16_f32 v62, v62, v63
	ds_write_b32 v174, v62 offset:12240
	v_cvt_pk_bf16_f32 v32, v32, v33
	ds_write_b32 v174, v32 offset:8832
	v_cvt_pk_bf16_f32 v34, v34, v35
	ds_write_b32 v174, v34 offset:9104
	v_cvt_pk_bf16_f32 v36, v36, v37
	ds_write_b32 v174, v36 offset:9920
	v_cvt_pk_bf16_f32 v38, v38, v39
	ds_write_b32 v174, v38 offset:10192
	v_cvt_pk_bf16_f32 v40, v40, v41
	ds_write_b32 v174, v40 offset:11008
	v_cvt_pk_bf16_f32 v42, v42, v43
	ds_write_b32 v174, v42 offset:11280
	v_cvt_pk_bf16_f32 v44, v44, v45
	ds_write_b32 v174, v44 offset:12096
	v_cvt_pk_bf16_f32 v46, v46, v47
	ds_write_b32 v174, v46 offset:12368
	v_cvt_pk_bf16_f32 v16, v16, v17
	ds_write_b32 v174, v16 offset:13056
	v_cvt_pk_bf16_f32 v18, v18, v19
	ds_write_b32 v174, v18 offset:13328
	v_cvt_pk_bf16_f32 v20, v20, v21
	ds_write_b32 v174, v20 offset:14144
	v_cvt_pk_bf16_f32 v22, v22, v23
	ds_write_b32 v174, v22 offset:14416
	v_cvt_pk_bf16_f32 v24, v24, v25
	ds_write_b32 v174, v24 offset:15232
	v_cvt_pk_bf16_f32 v26, v26, v27
	ds_write_b32 v174, v26 offset:15504
	v_cvt_pk_bf16_f32 v28, v28, v29
	ds_write_b32 v174, v28 offset:16320
	v_cvt_pk_bf16_f32 v30, v30, v31
	ds_write_b32 v174, v30 offset:16592
	v_cvt_pk_bf16_f32 v0, v0, v1
	ds_write_b32 v174, v0 offset:13184
	v_cvt_pk_bf16_f32 v2, v2, v3
	ds_write_b32 v174, v2 offset:13456
	v_cvt_pk_bf16_f32 v4, v4, v5
	ds_write_b32 v174, v4 offset:14272
	v_cvt_pk_bf16_f32 v6, v6, v7
	ds_write_b32 v174, v6 offset:14544
	v_cvt_pk_bf16_f32 v8, v8, v9
	ds_write_b32 v174, v8 offset:15360
	v_cvt_pk_bf16_f32 v10, v10, v11
	ds_write_b32 v174, v10 offset:15632
	v_cvt_pk_bf16_f32 v12, v12, v13
	ds_write_b32 v174, v12 offset:16448
	v_cvt_pk_bf16_f32 v14, v14, v15
	ds_write_b32 v174, v14 offset:16720
	s_cmp_ge_i32 s16, s22
	s_cselect_b64 s[40:41], -1, 0
	s_waitcnt lgkmcnt(0)
	ds_read_b128 v[182:185], v177 offset:0
	ds_read_b128 v[186:189], v177 offset:16
	ds_read_b128 v[190:193], v177 offset:2176
	ds_read_b128 v[194:197], v177 offset:2192
	s_waitcnt lgkmcnt(2)
	v_perm_b32 v198, v183, v182, v180
	v_perm_b32 v199, v185, v184, v180
	v_perm_b32 v200, v187, v186, v180
	v_perm_b32 v201, v189, v188, v180
	v_perm_b32 v206, v183, v182, v181
	v_perm_b32 v207, v185, v184, v181
	v_perm_b32 v208, v187, v186, v181
	v_perm_b32 v209, v189, v188, v181
	global_store_dwordx4 v178, v[198:201], s[42:43] sc1
	global_store_dwordx4 v179, v[206:209], s[42:43] sc1
	s_add_u32 s42, s42, 0x54000
	s_addc_u32 s43, s43, 0
	s_nop 1
	ds_read_b128 v[182:185], v177 offset:4352
	ds_read_b128 v[186:189], v177 offset:4368
	s_waitcnt lgkmcnt(2)
	v_perm_b32 v198, v191, v190, v180
	v_perm_b32 v199, v193, v192, v180
	v_perm_b32 v200, v195, v194, v180
	v_perm_b32 v201, v197, v196, v180
	v_perm_b32 v206, v191, v190, v181
	v_perm_b32 v207, v193, v192, v181
	v_perm_b32 v208, v195, v194, v181
	v_perm_b32 v209, v197, v196, v181
	global_store_dwordx4 v178, v[198:201], s[42:43] sc1
	global_store_dwordx4 v179, v[206:209], s[42:43] sc1
	s_add_u32 s42, s42, 0x54000
	s_addc_u32 s43, s43, 0
	s_nop 1
	ds_read_b128 v[190:193], v177 offset:6528
	ds_read_b128 v[194:197], v177 offset:6544
	s_waitcnt lgkmcnt(2)
	v_perm_b32 v198, v183, v182, v180
	v_perm_b32 v199, v185, v184, v180
	v_perm_b32 v200, v187, v186, v180
	v_perm_b32 v201, v189, v188, v180
	v_perm_b32 v206, v183, v182, v181
	v_perm_b32 v207, v185, v184, v181
	v_perm_b32 v208, v187, v186, v181
	v_perm_b32 v209, v189, v188, v181
	global_store_dwordx4 v178, v[198:201], s[42:43] sc1
	global_store_dwordx4 v179, v[206:209], s[42:43] sc1
	s_add_u32 s42, s42, 0x54000
	s_addc_u32 s43, s43, 0
	s_nop 1
	ds_read_b128 v[182:185], v177 offset:8704
	ds_read_b128 v[186:189], v177 offset:8720
	s_waitcnt lgkmcnt(2)
	v_perm_b32 v198, v191, v190, v180
	v_perm_b32 v199, v193, v192, v180
	v_perm_b32 v200, v195, v194, v180
	v_perm_b32 v201, v197, v196, v180
	v_perm_b32 v206, v191, v190, v181
	v_perm_b32 v207, v193, v192, v181
	v_perm_b32 v208, v195, v194, v181
	v_perm_b32 v209, v197, v196, v181
	global_store_dwordx4 v178, v[198:201], s[42:43] sc1
	global_store_dwordx4 v179, v[206:209], s[42:43] sc1
	s_add_u32 s42, s42, 0x54000
	s_addc_u32 s43, s43, 0
	s_nop 1
	ds_read_b128 v[190:193], v177 offset:10880
	ds_read_b128 v[194:197], v177 offset:10896
	s_waitcnt lgkmcnt(2)
	v_perm_b32 v198, v183, v182, v180
	v_perm_b32 v199, v185, v184, v180
	v_perm_b32 v200, v187, v186, v180
	v_perm_b32 v201, v189, v188, v180
	v_perm_b32 v206, v183, v182, v181
	v_perm_b32 v207, v185, v184, v181
	v_perm_b32 v208, v187, v186, v181
	v_perm_b32 v209, v189, v188, v181
	global_store_dwordx4 v178, v[198:201], s[42:43] sc1
	global_store_dwordx4 v179, v[206:209], s[42:43] sc1
	s_add_u32 s42, s42, 0x54000
	s_addc_u32 s43, s43, 0
	s_nop 1
	ds_read_b128 v[182:185], v177 offset:13056
	ds_read_b128 v[186:189], v177 offset:13072
	s_waitcnt lgkmcnt(2)
	v_perm_b32 v198, v191, v190, v180
	v_perm_b32 v199, v193, v192, v180
	v_perm_b32 v200, v195, v194, v180
	v_perm_b32 v201, v197, v196, v180
	v_perm_b32 v206, v191, v190, v181
	v_perm_b32 v207, v193, v192, v181
	v_perm_b32 v208, v195, v194, v181
	v_perm_b32 v209, v197, v196, v181
	global_store_dwordx4 v178, v[198:201], s[42:43] sc1
	global_store_dwordx4 v179, v[206:209], s[42:43] sc1
	s_add_u32 s42, s42, 0x54000
	s_addc_u32 s43, s43, 0
	s_nop 1
	ds_read_b128 v[190:193], v177 offset:15232
	ds_read_b128 v[194:197], v177 offset:15248
	s_waitcnt lgkmcnt(2)
	v_perm_b32 v198, v183, v182, v180
	v_perm_b32 v199, v185, v184, v180
	v_perm_b32 v200, v187, v186, v180
	v_perm_b32 v201, v189, v188, v180
	v_perm_b32 v206, v183, v182, v181
	v_perm_b32 v207, v185, v184, v181
	v_perm_b32 v208, v187, v186, v181
	v_perm_b32 v209, v189, v188, v181
	global_store_dwordx4 v178, v[198:201], s[42:43] sc1
	global_store_dwordx4 v179, v[206:209], s[42:43] sc1
	s_add_u32 s42, s42, 0x54000
	s_addc_u32 s43, s43, 0
	s_nop 1
	s_waitcnt lgkmcnt(0)
	s_barrier
	v_perm_b32 v198, v191, v190, v180
	v_perm_b32 v199, v193, v192, v180
	v_perm_b32 v200, v195, v194, v180
	v_perm_b32 v201, v197, v196, v180
	v_perm_b32 v206, v191, v190, v181
	v_perm_b32 v207, v193, v192, v181
	v_perm_b32 v208, v195, v194, v181
	v_perm_b32 v209, v197, v196, v181
	global_store_dwordx4 v178, v[198:201], s[42:43] sc1
	global_store_dwordx4 v179, v[206:209], s[42:43] sc1
	s_branch .LBB0_126
